# FFT final loop: second-iteration loads issued during the first iteration's arithmetic, each right after the consumer of the register it refills; in-loop load block removed
# baseline (speedup 1.0000x reference)
.LBB0_704:
.Lmy_ff_skip:
	s_waitcnt vmcnt(0)
	v_add_u32_e32 v82, s20, v24
	v_ashrrev_i32_e32 v83, 31, v82
	v_lshlrev_b64 v[4:5], 1, v[82:83]
	v_lshl_add_u64 v[20:21], s[30:31], 0, v[4:5]
	v_lshl_add_u64 v[6:7], s[2:3], 0, v[82:83]
	v_lshl_add_u64 v[4:5], s[86:87], 0, v[4:5]
	v_lshl_add_u64 v[6:7], v[6:7], 1, s[0:1]
	v_add_u32_e32 v54, 0xe00, v82
	v_ashrrev_i32_e32 v55, 31, v54
	v_lshl_add_u64 v[80:81], s[2:3], 0, v[54:55]
	v_lshl_add_u64 v[8:9], s[10:11], 0, v[82:83]
	v_lshl_add_u64 v[80:81], v[80:81], 1, s[0:1]
	v_add_u32_e32 v42, 0x200, v82
	v_ashrrev_i32_e32 v43, 31, v42
	v_lshl_add_u64 v[114:115], s[10:11], 0, v[54:55]
	v_lshl_add_u64 v[114:115], v[114:115], 1, s[0:1]
	v_add_u32_e32 v44, 0x400, v82
	v_ashrrev_i32_e32 v45, 31, v44
	v_add_u32_e32 v46, 0x600, v82
	v_ashrrev_i32_e32 v47, 31, v46
	v_add_u32_e32 v48, 0x800, v82
	v_ashrrev_i32_e32 v49, 31, v48
	v_add_u32_e32 v50, 0xa00, v82
	v_ashrrev_i32_e32 v51, 31, v50
	v_add_u32_e32 v52, 0xc00, v82
	v_ashrrev_i32_e32 v53, 31, v52
	v_lshl_add_u64 v[40:41], s[10:11], 0, v[52:53]
	v_lshl_add_u32 v111, s20, 3, v90
	s_movk_i32 s20, 0x1000
	s_and_b64 vcc, exec, s[12:13]
	s_mov_b64 s[12:13], 0
	v_lshlrev_b32_e32 v57, 16, v116
	s_cbranch_vccz .Lmy_fp_1
	v_add_u32_e32 v152, s20, v24
	v_ashrrev_i32_e32 v153, 31, v152
	v_lshlrev_b64 v[148:149], 1, v[152:153]
	v_lshl_add_u64 v[150:151], s[30:31], 0, v[148:149]
	global_load_ushort v116, v[150:151], off
.Lmy_fp_1:
	v_ashrrev_i32_e32 v81, 5, v82
	v_lshl_add_u32 v81, v81, 3, v111
	ds_read_b64 v[82:83], v81
	s_waitcnt lgkmcnt(0)
	v_mul_f32_e32 v81, 0x38800000, v82
	v_mul_f32_e32 v81, v0, v81
	v_fmac_f32_e32 v81, v2, v57
	v_lshlrev_b32_e32 v73, 16, v117
	s_cbranch_vccz .Lmy_fp_2
	v_add_u32_e32 v150, s20, v24
	v_ashrrev_i32_e32 v151, 31, v150
	v_lshl_add_u64 v[148:149], s[2:3], 0, v[150:151]
	v_lshl_add_u64 v[148:149], v[148:149], 1, s[0:1]
	global_load_ushort v117, v[148:149], off
.Lmy_fp_2:
	v_lshl_add_u64 v[6:7], v[8:9], 1, s[0:1]
	v_lshl_add_u64 v[8:9], s[2:3], 0, v[42:43]
	v_lshl_add_u64 v[8:9], v[8:9], 1, s[0:1]
	v_mul_f32_e32 v57, v81, v73
	v_bfe_u32 v73, v57, 16, 1
	v_add3_u32 v57, v57, v73, s45
	v_lshlrev_b32_e32 v56, 16, v118
	s_cbranch_vccz .Lmy_fp_3
	v_add_u32_e32 v150, s20, v24
	v_ashrrev_i32_e32 v151, 31, v150
	v_lshlrev_b64 v[148:149], 1, v[150:151]
	v_lshl_add_u64 v[148:149], s[86:87], 0, v[148:149]
	global_load_ushort v118, v[148:149], off
.Lmy_fp_3:
	v_lshlrev_b32_e32 v80, 16, v119
	s_cbranch_vccz .Lmy_fp_4
	v_add_u32_e32 v152, s20, v24
	v_add_u32_e32 v148, 0xe00, v152
	v_ashrrev_i32_e32 v149, 31, v148
	v_lshl_add_u64 v[150:151], s[2:3], 0, v[148:149]
	v_lshl_add_u64 v[150:151], v[150:151], 1, s[0:1]
	global_load_ushort v119, v[150:151], off
.Lmy_fp_4:
	v_lshl_add_u64 v[10:11], s[10:11], 0, v[42:43]
	v_lshlrev_b32_e32 v65, 16, v120
	s_cbranch_vccz .Lmy_fp_5
	v_add_u32_e32 v152, s20, v24
	v_ashrrev_i32_e32 v153, 31, v152
	v_lshl_add_u64 v[150:151], s[10:11], 0, v[152:153]
	v_lshl_add_u64 v[148:149], v[150:151], 1, s[0:1]
	global_load_ushort v120, v[148:149], off
.Lmy_fp_5:
	v_lshlrev_b64 v[6:7], 1, v[42:43]
	v_lshl_add_u64 v[22:23], s[30:31], 0, v[6:7]
	v_lshl_add_u64 v[6:7], s[86:87], 0, v[6:7]
	v_lshlrev_b32_e32 v74, 16, v121
	s_cbranch_vccz .Lmy_fp_6
	v_add_u32_e32 v152, s20, v24
	v_add_u32_e32 v150, 0x200, v152
	v_ashrrev_i32_e32 v151, 31, v150
	v_lshl_add_u64 v[148:149], s[2:3], 0, v[150:151]
	v_lshl_add_u64 v[148:149], v[148:149], 1, s[0:1]
	global_load_ushort v121, v[148:149], off
.Lmy_fp_6:
	v_lshl_add_u64 v[8:9], v[10:11], 1, s[0:1]
	v_lshl_add_u64 v[10:11], s[2:3], 0, v[44:45]
	v_lshl_add_u64 v[10:11], v[10:11], 1, s[0:1]
	v_lshlrev_b32_e32 v72, 16, v122
	s_cbranch_vccz .Lmy_fp_7
	v_add_u32_e32 v152, s20, v24
	v_add_u32_e32 v148, 0xe00, v152
	v_ashrrev_i32_e32 v149, 31, v148
	v_lshl_add_u64 v[150:151], s[10:11], 0, v[148:149]
	v_lshl_add_u64 v[150:151], v[150:151], 1, s[0:1]
	global_load_ushort v122, v[150:151], off
.Lmy_fp_7:
	v_lshlrev_b32_e32 v58, 16, v123
	s_cbranch_vccz .Lmy_fp_8
	v_add_u32_e32 v154, s20, v24
	v_add_u32_e32 v152, 0x200, v154
	v_ashrrev_i32_e32 v153, 31, v152
	v_lshlrev_b64 v[148:149], 1, v[152:153]
	v_lshl_add_u64 v[150:151], s[30:31], 0, v[148:149]
	global_load_ushort v123, v[150:151], off
.Lmy_fp_8:
	v_lshlrev_b32_e32 v66, 16, v124
	s_cbranch_vccz .Lmy_fp_9
	v_add_u32_e32 v154, s20, v24
	v_add_u32_e32 v152, 0x200, v154
	v_ashrrev_i32_e32 v153, 31, v152
	v_lshl_add_u64 v[150:151], s[10:11], 0, v[152:153]
	v_lshl_add_u64 v[148:149], v[150:151], 1, s[0:1]
	global_load_ushort v124, v[148:149], off
.Lmy_fp_9:
	v_lshlrev_b64 v[8:9], 1, v[44:45]
	v_lshl_add_u64 v[30:31], s[30:31], 0, v[8:9]
	v_lshl_add_u64 v[8:9], s[86:87], 0, v[8:9]
	v_lshlrev_b32_e32 v75, 16, v125
	s_cbranch_vccz .Lmy_fp_10
	v_add_u32_e32 v152, s20, v24
	v_add_u32_e32 v150, 0x400, v152
	v_ashrrev_i32_e32 v151, 31, v150
	v_lshl_add_u64 v[148:149], s[2:3], 0, v[150:151]
	v_lshl_add_u64 v[148:149], v[148:149], 1, s[0:1]
	global_load_ushort v125, v[148:149], off
.Lmy_fp_10:
	v_lshlrev_b32_e32 v43, 16, v126
	s_cbranch_vccz .Lmy_fp_11
	v_add_u32_e32 v152, s20, v24
	v_add_u32_e32 v150, 0x200, v152
	v_ashrrev_i32_e32 v151, 31, v150
	v_lshlrev_b64 v[148:149], 1, v[150:151]
	v_lshl_add_u64 v[148:149], s[86:87], 0, v[148:149]
	global_load_ushort v126, v[148:149], off
.Lmy_fp_11:
	v_lshl_add_u64 v[12:13], s[10:11], 0, v[44:45]
	v_lshl_add_u64 v[10:11], v[12:13], 1, s[0:1]
	v_lshl_add_u64 v[12:13], s[2:3], 0, v[46:47]
	v_lshl_add_u64 v[12:13], v[12:13], 1, s[0:1]
	v_lshlrev_b32_e32 v59, 16, v127
	s_cbranch_vccz .Lmy_fp_12
	v_add_u32_e32 v154, s20, v24
	v_add_u32_e32 v152, 0x400, v154
	v_ashrrev_i32_e32 v153, 31, v152
	v_lshlrev_b64 v[148:149], 1, v[152:153]
	v_lshl_add_u64 v[150:151], s[30:31], 0, v[148:149]
	global_load_ushort v127, v[150:151], off
.Lmy_fp_12:
	s_nop 0
	s_nop 0
	v_lshlrev_b32_e32 v45, 16, v128
	s_cbranch_vccz .Lmy_fp_13
	v_add_u32_e32 v152, s20, v24
	v_add_u32_e32 v150, 0x400, v152
	v_ashrrev_i32_e32 v151, 31, v150
	v_lshlrev_b64 v[148:149], 1, v[150:151]
	v_lshl_add_u64 v[148:149], s[86:87], 0, v[148:149]
	global_load_ushort v128, v[148:149], off
.Lmy_fp_13:
	v_lshl_add_u64 v[14:15], s[10:11], 0, v[46:47]
	v_lshlrev_b32_e32 v67, 16, v129
	s_cbranch_vccz .Lmy_fp_14
	v_add_u32_e32 v154, s20, v24
	v_add_u32_e32 v152, 0x400, v154
	v_ashrrev_i32_e32 v153, 31, v152
	v_lshl_add_u64 v[150:151], s[10:11], 0, v[152:153]
	v_lshl_add_u64 v[148:149], v[150:151], 1, s[0:1]
	global_load_ushort v129, v[148:149], off
.Lmy_fp_14:
	v_lshlrev_b64 v[10:11], 1, v[46:47]
	v_lshlrev_b32_e32 v76, 16, v130
	s_cbranch_vccz .Lmy_fp_15
	v_add_u32_e32 v152, s20, v24
	v_add_u32_e32 v150, 0x600, v152
	v_ashrrev_i32_e32 v151, 31, v150
	v_lshl_add_u64 v[148:149], s[2:3], 0, v[150:151]
	v_lshl_add_u64 v[148:149], v[148:149], 1, s[0:1]
	global_load_ushort v130, v[148:149], off
.Lmy_fp_15:
	v_lshl_add_u64 v[32:33], s[30:31], 0, v[10:11]
	v_lshl_add_u64 v[10:11], s[86:87], 0, v[10:11]
	v_lshl_add_u64 v[12:13], v[14:15], 1, s[0:1]
	v_lshl_add_u64 v[14:15], s[2:3], 0, v[48:49]
	v_lshl_add_u64 v[14:15], v[14:15], 1, s[0:1]
	v_lshlrev_b32_e32 v60, 16, v131
	s_cbranch_vccz .Lmy_fp_16
	v_add_u32_e32 v154, s20, v24
	v_add_u32_e32 v152, 0x600, v154
	v_ashrrev_i32_e32 v153, 31, v152
	v_lshlrev_b64 v[148:149], 1, v[152:153]
	v_lshl_add_u64 v[150:151], s[30:31], 0, v[148:149]
	global_load_ushort v131, v[150:151], off
.Lmy_fp_16:
	s_nop 0
	v_lshlrev_b32_e32 v68, 16, v132
	s_cbranch_vccz .Lmy_fp_17
	v_add_u32_e32 v154, s20, v24
	v_add_u32_e32 v152, 0x600, v154
	v_ashrrev_i32_e32 v153, 31, v152
	v_lshl_add_u64 v[150:151], s[10:11], 0, v[152:153]
	v_lshl_add_u64 v[148:149], v[150:151], 1, s[0:1]
	global_load_ushort v132, v[148:149], off
.Lmy_fp_17:
	v_lshlrev_b64 v[12:13], 1, v[48:49]
	v_lshl_add_u64 v[34:35], s[30:31], 0, v[12:13]
	v_lshl_add_u64 v[12:13], s[86:87], 0, v[12:13]
	v_lshlrev_b32_e32 v47, 16, v133
	s_cbranch_vccz .Lmy_fp_18
	v_add_u32_e32 v152, s20, v24
	v_add_u32_e32 v150, 0x600, v152
	v_ashrrev_i32_e32 v151, 31, v150
	v_lshlrev_b64 v[148:149], 1, v[150:151]
	v_lshl_add_u64 v[148:149], s[86:87], 0, v[148:149]
	global_load_ushort v133, v[148:149], off
.Lmy_fp_18:
	v_lshl_add_u64 v[16:17], s[10:11], 0, v[48:49]
	v_lshlrev_b32_e32 v77, 16, v134
	s_cbranch_vccz .Lmy_fp_19
	v_add_u32_e32 v152, s20, v24
	v_add_u32_e32 v150, 0x800, v152
	v_ashrrev_i32_e32 v151, 31, v150
	v_lshl_add_u64 v[148:149], s[2:3], 0, v[150:151]
	v_lshl_add_u64 v[148:149], v[148:149], 1, s[0:1]
	global_load_ushort v134, v[148:149], off
.Lmy_fp_19:
	v_lshl_add_u64 v[14:15], v[16:17], 1, s[0:1]
	v_lshl_add_u64 v[16:17], s[2:3], 0, v[50:51]
	v_lshl_add_u64 v[16:17], v[16:17], 1, s[0:1]
	v_lshlrev_b32_e32 v61, 16, v135
	s_cbranch_vccz .Lmy_fp_20
	v_add_u32_e32 v154, s20, v24
	v_add_u32_e32 v152, 0x800, v154
	v_ashrrev_i32_e32 v153, 31, v152
	v_lshlrev_b64 v[148:149], 1, v[152:153]
	v_lshl_add_u64 v[150:151], s[30:31], 0, v[148:149]
	global_load_ushort v135, v[150:151], off
.Lmy_fp_20:
	s_nop 0
	v_lshlrev_b32_e32 v69, 16, v136
	s_cbranch_vccz .Lmy_fp_21
	v_add_u32_e32 v154, s20, v24
	v_add_u32_e32 v152, 0x800, v154
	v_ashrrev_i32_e32 v153, 31, v152
	v_lshl_add_u64 v[150:151], s[10:11], 0, v[152:153]
	v_lshl_add_u64 v[148:149], v[150:151], 1, s[0:1]
	global_load_ushort v136, v[148:149], off
.Lmy_fp_21:
	v_lshlrev_b64 v[14:15], 1, v[50:51]
	v_lshlrev_b32_e32 v49, 16, v137
	s_cbranch_vccz .Lmy_fp_22
	v_add_u32_e32 v152, s20, v24
	v_add_u32_e32 v150, 0x800, v152
	v_ashrrev_i32_e32 v151, 31, v150
	v_lshlrev_b64 v[148:149], 1, v[150:151]
	v_lshl_add_u64 v[148:149], s[86:87], 0, v[148:149]
	global_load_ushort v137, v[148:149], off
.Lmy_fp_22:
	v_lshl_add_u64 v[18:19], s[10:11], 0, v[50:51]
	v_lshlrev_b32_e32 v78, 16, v138
	s_cbranch_vccz .Lmy_fp_23
	v_add_u32_e32 v152, s20, v24
	v_add_u32_e32 v150, 0xa00, v152
	v_ashrrev_i32_e32 v151, 31, v150
	v_lshl_add_u64 v[148:149], s[2:3], 0, v[150:151]
	v_lshl_add_u64 v[148:149], v[148:149], 1, s[0:1]
	global_load_ushort v138, v[148:149], off
.Lmy_fp_23:
	v_lshl_add_u64 v[36:37], s[30:31], 0, v[14:15]
	v_lshl_add_u64 v[14:15], s[86:87], 0, v[14:15]
	v_lshl_add_u64 v[16:17], v[18:19], 1, s[0:1]
	v_lshl_add_u64 v[18:19], s[2:3], 0, v[52:53]
	v_lshl_add_u64 v[18:19], v[18:19], 1, s[0:1]
	v_lshlrev_b32_e32 v62, 16, v139
	s_cbranch_vccz .Lmy_fp_24
	v_add_u32_e32 v154, s20, v24
	v_add_u32_e32 v152, 0xa00, v154
	v_ashrrev_i32_e32 v153, 31, v152
	v_lshlrev_b64 v[148:149], 1, v[152:153]
	v_lshl_add_u64 v[150:151], s[30:31], 0, v[148:149]
	global_load_ushort v139, v[150:151], off
.Lmy_fp_24:
	s_nop 0
	v_lshlrev_b32_e32 v70, 16, v140
	s_cbranch_vccz .Lmy_fp_25
	v_add_u32_e32 v154, s20, v24
	v_add_u32_e32 v152, 0xa00, v154
	v_ashrrev_i32_e32 v153, 31, v152
	v_lshl_add_u64 v[150:151], s[10:11], 0, v[152:153]
	v_lshl_add_u64 v[148:149], v[150:151], 1, s[0:1]
	global_load_ushort v140, v[148:149], off
.Lmy_fp_25:
	v_lshlrev_b64 v[16:17], 1, v[52:53]
	v_lshlrev_b32_e32 v51, 16, v141
	s_cbranch_vccz .Lmy_fp_26
	v_add_u32_e32 v152, s20, v24
	v_add_u32_e32 v150, 0xa00, v152
	v_ashrrev_i32_e32 v151, 31, v150
	v_lshlrev_b64 v[148:149], 1, v[150:151]
	v_lshl_add_u64 v[148:149], s[86:87], 0, v[148:149]
	global_load_ushort v141, v[148:149], off
.Lmy_fp_26:
	v_lshl_add_u64 v[38:39], s[30:31], 0, v[16:17]
	v_lshl_add_u64 v[16:17], s[86:87], 0, v[16:17]
	v_lshlrev_b32_e32 v79, 16, v142
	s_cbranch_vccz .Lmy_fp_27
	v_add_u32_e32 v152, s20, v24
	v_add_u32_e32 v150, 0xc00, v152
	v_ashrrev_i32_e32 v151, 31, v150
	v_lshl_add_u64 v[148:149], s[2:3], 0, v[150:151]
	v_lshl_add_u64 v[148:149], v[148:149], 1, s[0:1]
	global_load_ushort v142, v[148:149], off
.Lmy_fp_27:
	v_lshl_add_u64 v[18:19], v[40:41], 1, s[0:1]
	v_lshlrev_b32_e32 v63, 16, v143
	s_cbranch_vccz .Lmy_fp_28
	v_add_u32_e32 v154, s20, v24
	v_add_u32_e32 v152, 0xc00, v154
	v_ashrrev_i32_e32 v153, 31, v152
	v_lshlrev_b64 v[148:149], 1, v[152:153]
	v_lshl_add_u64 v[150:151], s[30:31], 0, v[148:149]
	global_load_ushort v143, v[150:151], off
.Lmy_fp_28:
	s_nop 0
	v_lshlrev_b32_e32 v53, 16, v144
	s_cbranch_vccz .Lmy_fp_29
	v_add_u32_e32 v152, s20, v24
	v_add_u32_e32 v150, 0xc00, v152
	v_ashrrev_i32_e32 v151, 31, v150
	v_lshlrev_b64 v[148:149], 1, v[150:151]
	v_lshl_add_u64 v[148:149], s[86:87], 0, v[148:149]
	global_load_ushort v144, v[148:149], off
.Lmy_fp_29:
	v_lshlrev_b32_e32 v71, 16, v145
	s_cbranch_vccz .Lmy_fp_30
	v_add_u32_e32 v154, s20, v24
	v_add_u32_e32 v152, 0xc00, v154
	v_ashrrev_i32_e32 v153, 31, v152
	v_lshl_add_u64 v[150:151], s[10:11], 0, v[152:153]
	v_lshl_add_u64 v[148:149], v[150:151], 1, s[0:1]
	global_load_ushort v145, v[148:149], off
.Lmy_fp_30:
	v_lshlrev_b64 v[18:19], 1, v[54:55]
	v_lshl_add_u64 v[40:41], s[30:31], 0, v[18:19]
	v_lshl_add_u64 v[18:19], s[86:87], 0, v[18:19]
	v_lshlrev_b32_e32 v64, 16, v146
	s_cbranch_vccz .Lmy_fp_31
	v_add_u32_e32 v154, s20, v24
	v_add_u32_e32 v152, 0xe00, v154
	v_ashrrev_i32_e32 v153, 31, v152
	v_lshlrev_b64 v[148:149], 1, v[152:153]
	v_lshl_add_u64 v[150:151], s[30:31], 0, v[148:149]
	global_load_ushort v146, v[150:151], off
.Lmy_fp_31:
	v_lshlrev_b32_e32 v55, 16, v147
	s_cbranch_vccz .Lmy_fp_32
	v_add_u32_e32 v152, s20, v24
	v_add_u32_e32 v150, 0xe00, v152
	v_ashrrev_i32_e32 v151, 31, v150
	v_lshlrev_b64 v[148:149], 1, v[150:151]
	v_lshl_add_u64 v[148:149], s[86:87], 0, v[148:149]
	global_load_ushort v147, v[148:149], off
.Lmy_fp_32:
	global_store_short_d16_hi v[20:21], v57, off
	v_mul_f32_e32 v20, 0x38800000, v83
	v_mul_f32_e32 v20, v25, v20
	v_fmac_f32_e32 v20, v3, v56
	v_mul_f32_e32 v20, v20, v65
	v_bfe_u32 v21, v20, 16, 1
	v_add3_u32 v20, v20, v21, s45
	global_store_short_d16_hi v[4:5], v20, off
	v_ashrrev_i32_e32 v4, 5, v42
	v_lshl_add_u32 v4, v4, 3, v111
	ds_read_b64 v[4:5], v4 offset:4096
	s_waitcnt lgkmcnt(0)
	v_mul_f32_e32 v4, 0x38800000, v4
	v_mul_f32_e32 v4, v0, v4
	v_fmac_f32_e32 v4, v2, v58
	v_mul_f32_e32 v4, v4, v74
	v_bfe_u32 v20, v4, 16, 1
	v_add3_u32 v4, v4, v20, s45
	global_store_short_d16_hi v[22:23], v4, off
	v_mul_f32_e32 v4, 0x38800000, v5
	v_mul_f32_e32 v4, v25, v4
	v_fmac_f32_e32 v4, v3, v43
	v_mul_f32_e32 v4, v4, v66
	v_bfe_u32 v5, v4, 16, 1
	v_add3_u32 v4, v4, v5, s45
	global_store_short_d16_hi v[6:7], v4, off
	v_ashrrev_i32_e32 v4, 5, v44
	v_lshl_add_u32 v4, v4, 3, v111
	ds_read_b64 v[4:5], v4 offset:8192
	s_waitcnt lgkmcnt(0)
	v_mul_f32_e32 v4, 0x38800000, v4
	v_mul_f32_e32 v4, v0, v4
	v_fmac_f32_e32 v4, v2, v59
	v_mul_f32_e32 v4, v4, v75
	v_bfe_u32 v6, v4, 16, 1
	v_add3_u32 v4, v4, v6, s45
	global_store_short_d16_hi v[30:31], v4, off
	v_mul_f32_e32 v4, 0x38800000, v5
	v_mul_f32_e32 v4, v25, v4
	v_fmac_f32_e32 v4, v3, v45
	v_mul_f32_e32 v4, v4, v67
	v_bfe_u32 v5, v4, 16, 1
	v_add3_u32 v4, v4, v5, s45
	global_store_short_d16_hi v[8:9], v4, off
	v_ashrrev_i32_e32 v4, 5, v46
	v_lshl_add_u32 v4, v4, 3, v111
	ds_read_b64 v[4:5], v4 offset:12288
	s_waitcnt lgkmcnt(0)
	v_mul_f32_e32 v4, 0x38800000, v4
	v_mul_f32_e32 v4, v0, v4
	v_fmac_f32_e32 v4, v2, v60
	v_mul_f32_e32 v4, v4, v76
	v_bfe_u32 v6, v4, 16, 1
	v_add3_u32 v4, v4, v6, s45
	global_store_short_d16_hi v[32:33], v4, off
	v_mul_f32_e32 v4, 0x38800000, v5
	v_mul_f32_e32 v4, v25, v4
	v_fmac_f32_e32 v4, v3, v47
	v_mul_f32_e32 v4, v4, v68
	v_bfe_u32 v5, v4, 16, 1
	v_add3_u32 v4, v4, v5, s45
	global_store_short_d16_hi v[10:11], v4, off
	v_ashrrev_i32_e32 v4, 5, v48
	v_lshl_add_u32 v4, v4, 3, v111
	ds_read_b64 v[4:5], v4 offset:16384
	s_waitcnt lgkmcnt(0)
	v_mul_f32_e32 v4, 0x38800000, v4
	v_mul_f32_e32 v4, v0, v4
	v_fmac_f32_e32 v4, v2, v61
	v_mul_f32_e32 v4, v4, v77
	v_bfe_u32 v6, v4, 16, 1
	v_add3_u32 v4, v4, v6, s45
	global_store_short_d16_hi v[34:35], v4, off
	v_mul_f32_e32 v4, 0x38800000, v5
	v_mul_f32_e32 v4, v25, v4
	v_fmac_f32_e32 v4, v3, v49
	v_mul_f32_e32 v4, v4, v69
	v_bfe_u32 v5, v4, 16, 1
	v_add3_u32 v4, v4, v5, s45
	global_store_short_d16_hi v[12:13], v4, off
	v_ashrrev_i32_e32 v4, 5, v50
	v_lshl_add_u32 v4, v4, 3, v111
	ds_read_b64 v[4:5], v4 offset:20480
	s_waitcnt lgkmcnt(0)
	v_mul_f32_e32 v4, 0x38800000, v4
	v_mul_f32_e32 v4, v0, v4
	v_fmac_f32_e32 v4, v2, v62
	v_mul_f32_e32 v4, v4, v78
	v_bfe_u32 v6, v4, 16, 1
	v_add3_u32 v4, v4, v6, s45
	global_store_short_d16_hi v[36:37], v4, off
	v_mul_f32_e32 v4, 0x38800000, v5
	v_mul_f32_e32 v4, v25, v4
	v_fmac_f32_e32 v4, v3, v51
	v_mul_f32_e32 v4, v4, v70
	v_bfe_u32 v5, v4, 16, 1
	v_add3_u32 v4, v4, v5, s45
	global_store_short_d16_hi v[14:15], v4, off
	v_ashrrev_i32_e32 v4, 5, v52
	v_lshl_add_u32 v4, v4, 3, v111
	ds_read_b64 v[4:5], v4 offset:24576
	s_waitcnt lgkmcnt(0)
	v_mul_f32_e32 v4, 0x38800000, v4
	v_mul_f32_e32 v4, v0, v4
	v_fmac_f32_e32 v4, v2, v63
	v_mul_f32_e32 v4, v4, v79
	v_bfe_u32 v6, v4, 16, 1
	v_add3_u32 v4, v4, v6, s45
	global_store_short_d16_hi v[38:39], v4, off
	v_mul_f32_e32 v4, 0x38800000, v5
	v_mul_f32_e32 v4, v25, v4
	v_fmac_f32_e32 v4, v3, v53
	v_mul_f32_e32 v4, v4, v71
	v_bfe_u32 v5, v4, 16, 1
	v_add3_u32 v4, v4, v5, s45
	global_store_short_d16_hi v[16:17], v4, off
	v_ashrrev_i32_e32 v4, 5, v54
	v_lshl_add_u32 v4, v4, 3, v111
	ds_read_b64 v[4:5], v4 offset:28672
	s_waitcnt lgkmcnt(0)
	v_mul_f32_e32 v4, 0x38800000, v4
	v_mul_f32_e32 v4, v0, v4
	v_fmac_f32_e32 v4, v2, v64
	v_mul_f32_e32 v4, v4, v80
	v_bfe_u32 v6, v4, 16, 1
	v_add3_u32 v4, v4, v6, s45
	global_store_short_d16_hi v[40:41], v4, off
	v_mul_f32_e32 v4, 0x38800000, v5
	v_mul_f32_e32 v4, v25, v4
	v_fmac_f32_e32 v4, v3, v55
	v_mul_f32_e32 v4, v4, v72
	v_bfe_u32 v5, v4, 16, 1
	v_add3_u32 v4, v4, v5, s45
	global_store_short_d16_hi v[18:19], v4, off
	s_cbranch_vccnz .LBB0_704
	v_readlane_b32 s2, v253, 3
	s_add_i32 s33, s33, s2
	s_cmpk_gt_i32 s33, 0x1ff
	s_barrier
	v_readlane_b32 s3, v253, 4
	s_cbranch_scc0 .LBB0_617
